# FFN gate/up GEMM K-loop: LDS-DMA staging loads use SGPR-base+VGPR-offset addressing (12 of 16 v_lshl_add_u64 per iteration removed), B-fragment LDS base kept in one register (4 v_add_u32 per iteration
# baseline (speedup 1.0000x reference)
; #define PG8_STAGE(bufoff, gbase, voff) do { _Pragma("unroll") for (int _i = 0; _i < 2; ++_i) \
;         __builtin_amdgcn_global_load_lds((const unsigned*)((const char*)(gbase) + (voff)[_i]), (PG8_LAS unsigned*)(lds + (bufoff) + ldsw + _i * 8192), 16, 0, 0); } while (0)
; #define PG8_LDA(dst, b, h) do { _Pragma("unroll") for (int m = 0; m < 4; ++m) _Pragma("unroll") for (int k = 0; k < 2; ++k) dst[m][k] = *(const PG8_LAS bf16x8*)(lds + PG8_SA(b, h) + aoff + m * 2048 + k * 1024); } while (0)
; #define PG8_LDB(dst, b, h) do { _Pragma("unroll") for (int n = 0; n < 2; ++n) _Pragma("unroll") for (int k = 0; k < 2; ++k) dst[n][k] = *(const PG8_LAS bf16x8*)(lds + PG8_SB(b, h) + boff + n * 2048 + k * 1024); } while (0)
; #define PG8_MMA(ai, bj, At, Bt) do { __builtin_amdgcn_s_setprio(1); _Pragma("unroll") for (int m = 0; m < 4; ++m) _Pragma("unroll") for (int n = 0; n < 2; ++n) _Pragma("unroll") for (int k = 0; k < 2; ++k) \
;         acc[ai][bj][m][n] = __builtin_amdgcn_mfma_f32_16x16x32_bf16(Bt[n][k], At[m][k], acc[ai][bj][m][n], 0, 0, 0); __builtin_amdgcn_s_setprio(0); } while (0)
; #define PG8_WAIT_V(n) asm volatile("s_waitcnt vmcnt(" #n ")" ::: "memory")
; template <class Epi, class Sched, bool ALIGN_EPI = false, bool SP2 = false>
; __device__ __forceinline__ void gemm_phase(PG8_LAS unsigned char* lds, const Gemm g, const Sched& S, const Epi& E) {
;     ...
;     f32x4 acc[2][2][4][2];
; #pragma unroll
;     for (int a = 0; a < 2; ++a)
; #pragma unroll
;         for (int b = 0; b < 2; ++b)
; #pragma unroll
;             for (int m = 0; m < 4; ++m)
; #pragma unroll
;                 for (int n = 0; n < 2; ++n) acc[a][b][m][n] = (f32x4){0.f, 0.f, 0.f, 0.f};
;     ...
;         for (int t = 0; t < nt; t += 2) {
;             const bool last = (t == nt - 2);
;             const char* a1 = cA + (size_t)(t + 1) * kstep;
;             const char* a2 = last ? nA : cA + (size_t)(t + 2) * kstep; const char* b2 = last ? nB : cB + (size_t)(t + 2) * kstep;
;             const char* a3 = a2 + kstep; const char* b3 = b2 + kstep;
;             if (last && has_next) S.a_ready(nxt);
;             if constexpr (SP2) {
;             PG8_LDB(B0, 0, 0); PG8_LDB(B1, 0, 1); PG8_SCHED; PG8_LDA(At, 0, 0); PG8_STAGE(PG8_SA(1, 1), a1 + hstep, voffA);
;             PG8_WAIT_V(8); PG8_WAIT_L(0); PG8_BAR; PG8_MMA(0, 0, At, B0); PG8_MMA(0, 1, At, B1); PG8_BAR; PG8_SCHED;
.LBB0_416:
	s_ashr_i32 s43, s42, 31
	s_lshl_b64 s[0:1], s[42:43], 20
	v_readlane_b32 s4, v254, 59
	v_readlane_b32 s5, v254, 60
	s_add_u32 s56, s4, s0
	s_addc_u32 s57, s5, s1
	s_and_b64 s[0:1], s[38:39], exec
	s_cselect_b32 s7, s57, s65
	s_cselect_b32 s8, s56, s64
	s_ashr_i32 s37, s36, 31
	s_lshl_b64 s[0:1], s[36:37], 20
	s_add_u32 s62, s59, s0
	s_addc_u32 s63, s66, s1
	s_and_b64 s[0:1], s[38:39], exec
	s_cselect_b32 s9, s63, s41
	s_cselect_b32 s14, s62, s40
	s_add_u32 s15, s40, 0x100
	s_addc_u32 s17, s41, 0
	s_add_u32 s40, s64, 0x80080
	v_mov_b32_e32 v0, 0
	s_addc_u32 s41, s65, 0
	s_mov_b32 s19, -2
	v_mov_b32_e32 v1, v0
	v_mov_b32_e32 v2, v0
	v_mov_b32_e32 v3, v0
	v_mov_b32_e32 v4, v0
	v_mov_b32_e32 v5, v0
	v_mov_b32_e32 v6, v0
	v_mov_b32_e32 v7, v0
	v_mov_b32_e32 v16, v0
	v_mov_b32_e32 v17, v0
	v_mov_b32_e32 v18, v0
	v_mov_b32_e32 v19, v0
	v_mov_b32_e32 v20, v0
	v_mov_b32_e32 v21, v0
	v_mov_b32_e32 v22, v0
	v_mov_b32_e32 v23, v0
	v_mov_b32_e32 v32, v0
	v_mov_b32_e32 v33, v0
	v_mov_b32_e32 v34, v0
	v_mov_b32_e32 v35, v0
	v_mov_b32_e32 v36, v0
	v_mov_b32_e32 v37, v0
	v_mov_b32_e32 v38, v0
	v_mov_b32_e32 v39, v0
	v_mov_b32_e32 v48, v0
	v_mov_b32_e32 v49, v0
	v_mov_b32_e32 v50, v0
	v_mov_b32_e32 v51, v0
	v_mov_b32_e32 v52, v0
	v_mov_b32_e32 v53, v0
	v_mov_b32_e32 v54, v0
	v_mov_b32_e32 v55, v0
	v_mov_b32_e32 v8, v0
	v_mov_b32_e32 v9, v0
	v_mov_b32_e32 v10, v0
	v_mov_b32_e32 v11, v0
	v_mov_b32_e32 v12, v0
	v_mov_b32_e32 v13, v0
	v_mov_b32_e32 v14, v0
	v_mov_b32_e32 v15, v0
	v_mov_b32_e32 v24, v0
	v_mov_b32_e32 v25, v0
	v_mov_b32_e32 v26, v0
	v_mov_b32_e32 v27, v0
	v_mov_b32_e32 v28, v0
	v_mov_b32_e32 v29, v0
	v_mov_b32_e32 v30, v0
	v_mov_b32_e32 v31, v0
	v_mov_b32_e32 v40, v0
	v_mov_b32_e32 v41, v0
	v_mov_b32_e32 v42, v0
	v_mov_b32_e32 v43, v0
	v_mov_b32_e32 v44, v0
	v_mov_b32_e32 v45, v0
	v_mov_b32_e32 v46, v0
	v_mov_b32_e32 v47, v0
	v_mov_b32_e32 v56, v0
	v_mov_b32_e32 v57, v0
	v_mov_b32_e32 v58, v0
	v_mov_b32_e32 v59, v0
	v_mov_b32_e32 v60, v0
	v_mov_b32_e32 v61, v0
	v_mov_b32_e32 v62, v0
	v_mov_b32_e32 v63, v0
	v_mov_b32_e32 v64, v0
	v_mov_b32_e32 v65, v0
	v_mov_b32_e32 v66, v0
	v_mov_b32_e32 v67, v0
	v_mov_b32_e32 v68, v0
	v_mov_b32_e32 v69, v0
	v_mov_b32_e32 v70, v0
	v_mov_b32_e32 v71, v0
	v_mov_b32_e32 v80, v0
	v_mov_b32_e32 v81, v0
	v_mov_b32_e32 v82, v0
	v_mov_b32_e32 v83, v0
	v_mov_b32_e32 v84, v0
	v_mov_b32_e32 v85, v0
	v_mov_b32_e32 v86, v0
	v_mov_b32_e32 v87, v0
	v_mov_b32_e32 v98, v0
	v_mov_b32_e32 v99, v0
	v_mov_b32_e32 v100, v0
	v_mov_b32_e32 v101, v0
	v_mov_b32_e32 v102, v0
	v_mov_b32_e32 v103, v0
	v_mov_b32_e32 v104, v0
	v_mov_b32_e32 v105, v0
	v_mov_b32_e32 v114, v0
	v_mov_b32_e32 v115, v0
	v_mov_b32_e32 v116, v0
	v_mov_b32_e32 v117, v0
	v_mov_b32_e32 v118, v0
	v_mov_b32_e32 v119, v0
	v_mov_b32_e32 v120, v0
	v_mov_b32_e32 v121, v0
	v_mov_b32_e32 v72, v0
	v_mov_b32_e32 v73, v0
	v_mov_b32_e32 v74, v0
	v_mov_b32_e32 v75, v0
	v_mov_b32_e32 v76, v0
	v_mov_b32_e32 v77, v0
	v_mov_b32_e32 v78, v0
	v_mov_b32_e32 v79, v0
	v_mov_b32_e32 v88, v0
	v_mov_b32_e32 v89, v0
	v_mov_b32_e32 v90, v0
	v_mov_b32_e32 v91, v0
	v_mov_b32_e32 v92, v0
	v_mov_b32_e32 v93, v0
	v_mov_b32_e32 v94, v0
	v_mov_b32_e32 v95, v0
	v_mov_b32_e32 v106, v0
	v_mov_b32_e32 v107, v0
	v_mov_b32_e32 v108, v0
	v_mov_b32_e32 v109, v0
	v_mov_b32_e32 v110, v0
	v_mov_b32_e32 v111, v0
	v_mov_b32_e32 v112, v0
	v_mov_b32_e32 v113, v0
	v_mov_b32_e32 v122, v0
	v_mov_b32_e32 v123, v0
	v_mov_b32_e32 v124, v0
	v_mov_b32_e32 v125, v0
	v_mov_b32_e32 v126, v0
	v_mov_b32_e32 v127, v0
	v_mov_b32_e32 v128, v0
	v_mov_b32_e32 v129, v0
	v_add_u32_e32 v250, 0x10000, v203
.LBB0_417:
	s_add_u32 s0, s40, 0xfff80080
	s_addc_u32 s1, s41, -1
	s_add_i32 s30, 0, 0x10000
	s_cmp_eq_u32 s19, 28
	s_cselect_b32 s5, s7, s1
	s_cselect_b32 s4, s8, s0
	s_cselect_b32 s1, s9, s17
	s_cselect_b32 s0, s14, s15
	s_add_i32 s33, 0, 0x14000
	ds_read_b128 v[130:133], v250
	ds_read_b128 v[134:137], v250 offset:1024
	ds_read_b128 v[138:141], v250 offset:2048
	ds_read_b128 v[142:145], v250 offset:3072
	ds_read_b128 v[146:149], v250 offset:16384
	ds_read_b128 v[150:153], v250 offset:17408
	ds_read_b128 v[154:157], v250 offset:18432
	ds_read_b128 v[158:161], v250 offset:19456
	s_add_i32 m0, s67, 0xc000
	ds_read_b128 v[162:165], v209
	ds_read_b128 v[166:169], v209 offset:1024
	ds_read_b128 v[170:173], v209 offset:2048
	ds_read_b128 v[174:177], v209 offset:3072
	ds_read_b128 v[210:213], v209 offset:4096
	ds_read_b128 v[232:235], v209 offset:5120
	ds_read_b128 v[242:245], v209 offset:6144
	ds_read_b128 v[246:249], v209 offset:7168
	global_load_lds_dwordx4 v188, s[40:41]
	s_add_i32 m0, s67, 0xe000
	s_nop 0
	global_load_lds_dwordx4 v186, s[40:41]
	s_waitcnt vmcnt(8)
	s_waitcnt lgkmcnt(0)
	s_barrier
; #define PG8_STAGE(bufoff, gbase, voff) do { _Pragma("unroll") for (int _i = 0; _i < 2; ++_i) \
;         __builtin_amdgcn_global_load_lds((const unsigned*)((const char*)(gbase) + (voff)[_i]), (PG8_LAS unsigned*)(lds + (bufoff) + ldsw + _i * 8192), 16, 0, 0); } while (0)
; #define PG8_LDA(dst, b, h) do { _Pragma("unroll") for (int m = 0; m < 4; ++m) _Pragma("unroll") for (int k = 0; k < 2; ++k) dst[m][k] = *(const PG8_LAS bf16x8*)(lds + PG8_SA(b, h) + aoff + m * 2048 + k * 1024); } while (0)
; #define PG8_MMA(ai, bj, At, Bt) do { __builtin_amdgcn_s_setprio(1); _Pragma("unroll") for (int m = 0; m < 4; ++m) _Pragma("unroll") for (int n = 0; n < 2; ++n) _Pragma("unroll") for (int k = 0; k < 2; ++k) \
;         acc[ai][bj][m][n] = __builtin_amdgcn_mfma_f32_16x16x32_bf16(Bt[n][k], At[m][k], acc[ai][bj][m][n], 0, 0, 0); __builtin_amdgcn_s_setprio(0); } while (0)
; #define PG8_WAIT_V(n) asm volatile("s_waitcnt vmcnt(" #n ")" ::: "memory")
; #define PG8_WAIT_L(n) asm volatile("s_waitcnt lgkmcnt(" #n ")" ::: "memory")
; #define PG8_BAR __builtin_amdgcn_s_barrier()
; #define PG8_SCHED __builtin_amdgcn_sched_barrier(0)
; template <class Epi, class Sched, bool ALIGN_EPI = false, bool SP2 = false>
; __device__ __forceinline__ void gemm_phase(PG8_LAS unsigned char* lds, const Gemm g, const Sched& S, const Epi& E) {
;     ...
;             PG8_WAIT_V(8); PG8_WAIT_L(0); PG8_BAR; PG8_MMA(0, 0, At, B0); PG8_MMA(0, 1, At, B1); PG8_BAR; PG8_SCHED;
;             PG8_LDA(At, 0, 1); PG8_STAGE(PG8_SB(0, 0), b2, voffB); PG8_STAGE(PG8_SB(0, 1), b2 + hstep, voffB); PG8_STAGE(PG8_SA(0, 0), a2, voffA);
;             PG8_WAIT_V(8); PG8_WAIT_L(0); PG8_BAR; PG8_MMA(1, 0, At, B0); PG8_MMA(1, 1, At, B1); PG8_BAR; PG8_SCHED;
	v_mfma_f32_16x16x32_bf16 v[126:129], v[130:133], v[162:165], v[126:129]
	v_mfma_f32_16x16x32_bf16 v[122:125], v[138:141], v[162:165], v[122:125]
	v_mfma_f32_16x16x32_bf16 v[110:113], v[130:133], v[170:173], v[110:113]
	v_mfma_f32_16x16x32_bf16 v[106:109], v[138:141], v[170:173], v[106:109]
	v_mfma_f32_16x16x32_bf16 v[92:95], v[130:133], v[210:213], v[92:95]
	v_mfma_f32_16x16x32_bf16 v[88:91], v[138:141], v[210:213], v[88:91]
	v_mfma_f32_16x16x32_bf16 v[76:79], v[130:133], v[242:245], v[76:79]
	v_mfma_f32_16x16x32_bf16 v[72:75], v[138:141], v[242:245], v[72:75]
	v_mfma_f32_16x16x32_bf16 v[126:129], v[134:137], v[166:169], v[126:129]
	v_mfma_f32_16x16x32_bf16 v[122:125], v[142:145], v[166:169], v[122:125]
	v_mfma_f32_16x16x32_bf16 v[110:113], v[134:137], v[174:177], v[110:113]
	v_mfma_f32_16x16x32_bf16 v[106:109], v[142:145], v[174:177], v[106:109]
	v_mfma_f32_16x16x32_bf16 v[92:95], v[134:137], v[232:235], v[92:95]
	v_mfma_f32_16x16x32_bf16 v[88:91], v[142:145], v[232:235], v[88:91]
	v_mfma_f32_16x16x32_bf16 v[76:79], v[134:137], v[246:249], v[76:79]
	v_mfma_f32_16x16x32_bf16 v[72:75], v[142:145], v[246:249], v[72:75]
	v_mfma_f32_16x16x32_bf16 v[118:121], v[146:149], v[162:165], v[118:121]
	v_mfma_f32_16x16x32_bf16 v[114:117], v[154:157], v[162:165], v[114:117]
	v_mfma_f32_16x16x32_bf16 v[102:105], v[146:149], v[170:173], v[102:105]
	v_mfma_f32_16x16x32_bf16 v[98:101], v[154:157], v[170:173], v[98:101]
	v_mfma_f32_16x16x32_bf16 v[84:87], v[146:149], v[210:213], v[84:87]
	v_mfma_f32_16x16x32_bf16 v[80:83], v[154:157], v[210:213], v[80:83]
	v_mfma_f32_16x16x32_bf16 v[68:71], v[146:149], v[242:245], v[68:71]
	v_mfma_f32_16x16x32_bf16 v[64:67], v[154:157], v[242:245], v[64:67]
	v_mfma_f32_16x16x32_bf16 v[118:121], v[150:153], v[166:169], v[118:121]
	v_mfma_f32_16x16x32_bf16 v[114:117], v[158:161], v[166:169], v[114:117]
	v_mfma_f32_16x16x32_bf16 v[102:105], v[150:153], v[174:177], v[102:105]
	v_mfma_f32_16x16x32_bf16 v[98:101], v[158:161], v[174:177], v[98:101]
	v_mfma_f32_16x16x32_bf16 v[84:87], v[150:153], v[232:235], v[84:87]
	v_mfma_f32_16x16x32_bf16 v[80:83], v[158:161], v[232:235], v[80:83]
	v_mfma_f32_16x16x32_bf16 v[68:71], v[150:153], v[246:249], v[68:71]
	v_mfma_f32_16x16x32_bf16 v[64:67], v[158:161], v[246:249], v[64:67]
	s_barrier
	s_add_i32 s30, s30, s28
	s_mov_b32 m0, s30
	ds_read_b128 v[162:165], v209 offset:16384
	ds_read_b128 v[166:169], v209 offset:17408
	ds_read_b128 v[170:173], v209 offset:18432
	ds_read_b128 v[174:177], v209 offset:19456
	ds_read_b128 v[210:213], v209 offset:20480
	ds_read_b128 v[232:235], v209 offset:21504
	ds_read_b128 v[242:245], v209 offset:22528
	ds_read_b128 v[246:249], v209 offset:23552
	global_load_lds_dwordx4 v96, s[0:1]
	s_add_i32 m0, s30, 0x2000
	s_add_u32 s30, s0, 0x80000
	s_addc_u32 s31, s1, 0
	s_add_i32 s33, s33, s28
	global_load_lds_dwordx4 v178, s[0:1]
	s_mov_b32 m0, s33
	v_lshl_add_u64 v[228:229], s[4:5], 0, v[180:181]
	global_load_lds_dwordx4 v96, s[30:31]
	s_add_i32 m0, s33, 0x2000
	s_nop 0
	global_load_lds_dwordx4 v178, s[30:31]
	v_lshl_add_u64 v[214:215], s[4:5], 0, v[182:183]
	s_mov_b32 m0, s67
	s_nop 0
	global_load_lds_dwordx4 v[214:215], off
	s_mov_b32 m0, s68
	s_nop 0
	global_load_lds_dwordx4 v[228:229], off
	s_waitcnt vmcnt(8)
	s_waitcnt lgkmcnt(0)
	s_barrier
	v_mfma_f32_16x16x32_bf16 v[60:63], v[130:133], v[162:165], v[60:63]
	v_mfma_f32_16x16x32_bf16 v[56:59], v[138:141], v[162:165], v[56:59]
	v_mfma_f32_16x16x32_bf16 v[44:47], v[130:133], v[170:173], v[44:47]
	v_mfma_f32_16x16x32_bf16 v[40:43], v[138:141], v[170:173], v[40:43]
	v_mfma_f32_16x16x32_bf16 v[28:31], v[130:133], v[210:213], v[28:31]
	v_mfma_f32_16x16x32_bf16 v[24:27], v[138:141], v[210:213], v[24:27]
	v_mfma_f32_16x16x32_bf16 v[12:15], v[130:133], v[242:245], v[12:15]
	v_mfma_f32_16x16x32_bf16 v[8:11], v[138:141], v[242:245], v[8:11]
	v_mfma_f32_16x16x32_bf16 v[60:63], v[134:137], v[166:169], v[60:63]
	v_mfma_f32_16x16x32_bf16 v[56:59], v[142:145], v[166:169], v[56:59]
	v_mfma_f32_16x16x32_bf16 v[44:47], v[134:137], v[174:177], v[44:47]
	v_mfma_f32_16x16x32_bf16 v[40:43], v[142:145], v[174:177], v[40:43]
	v_mfma_f32_16x16x32_bf16 v[28:31], v[134:137], v[232:235], v[28:31]
	v_mfma_f32_16x16x32_bf16 v[24:27], v[142:145], v[232:235], v[24:27]
	v_mfma_f32_16x16x32_bf16 v[12:15], v[134:137], v[246:249], v[12:15]
	v_mfma_f32_16x16x32_bf16 v[8:11], v[142:145], v[246:249], v[8:11]
	v_mfma_f32_16x16x32_bf16 v[52:55], v[146:149], v[162:165], v[52:55]
	v_mfma_f32_16x16x32_bf16 v[48:51], v[154:157], v[162:165], v[48:51]
	v_mfma_f32_16x16x32_bf16 v[36:39], v[146:149], v[170:173], v[36:39]
	v_mfma_f32_16x16x32_bf16 v[32:35], v[154:157], v[170:173], v[32:35]
	v_mfma_f32_16x16x32_bf16 v[20:23], v[146:149], v[210:213], v[20:23]
	v_mfma_f32_16x16x32_bf16 v[16:19], v[154:157], v[210:213], v[16:19]
	v_mfma_f32_16x16x32_bf16 v[4:7], v[146:149], v[242:245], v[4:7]
	v_mfma_f32_16x16x32_bf16 v[0:3], v[154:157], v[242:245], v[0:3]
	v_mfma_f32_16x16x32_bf16 v[52:55], v[150:153], v[166:169], v[52:55]
	v_mfma_f32_16x16x32_bf16 v[48:51], v[158:161], v[166:169], v[48:51]
	v_mfma_f32_16x16x32_bf16 v[36:39], v[150:153], v[174:177], v[36:39]
	v_mfma_f32_16x16x32_bf16 v[32:35], v[158:161], v[174:177], v[32:35]
	v_mfma_f32_16x16x32_bf16 v[20:23], v[150:153], v[232:235], v[20:23]
	v_mfma_f32_16x16x32_bf16 v[16:19], v[158:161], v[232:235], v[16:19]
	v_mfma_f32_16x16x32_bf16 v[4:7], v[150:153], v[246:249], v[4:7]
	v_mfma_f32_16x16x32_bf16 v[0:3], v[158:161], v[246:249], v[0:3]
	s_barrier
; #define PG8_STAGE(bufoff, gbase, voff) do { _Pragma("unroll") for (int _i = 0; _i < 2; ++_i) \
;         __builtin_amdgcn_global_load_lds((const unsigned*)((const char*)(gbase) + (voff)[_i]), (PG8_LAS unsigned*)(lds + (bufoff) + ldsw + _i * 8192), 16, 0, 0); } while (0)
; #define PG8_LDA(dst, b, h) do { _Pragma("unroll") for (int m = 0; m < 4; ++m) _Pragma("unroll") for (int k = 0; k < 2; ++k) dst[m][k] = *(const PG8_LAS bf16x8*)(lds + PG8_SA(b, h) + aoff + m * 2048 + k * 1024); } while (0)
; #define PG8_LDB(dst, b, h) do { _Pragma("unroll") for (int n = 0; n < 2; ++n) _Pragma("unroll") for (int k = 0; k < 2; ++k) dst[n][k] = *(const PG8_LAS bf16x8*)(lds + PG8_SB(b, h) + boff + n * 2048 + k * 1024); } while (0)
; template <class Epi, class Sched, bool ALIGN_EPI = false, bool SP2 = false>
; __device__ __forceinline__ void gemm_phase(PG8_LAS unsigned char* lds, const Gemm g, const Sched& S, const Epi& E) {
;     ...
;         for (int t = 0; t < nt; t += 2) {
;             const bool last = (t == nt - 2);
;             const char* a1 = cA + (size_t)(t + 1) * kstep;
;             const char* a2 = last ? nA : cA + (size_t)(t + 2) * kstep; const char* b2 = last ? nB : cB + (size_t)(t + 2) * kstep;
;             const char* a3 = a2 + kstep; const char* b3 = b2 + kstep;
;             if (last && has_next) S.a_ready(nxt);
;             if constexpr (SP2) {
;             PG8_LDB(B0, 0, 0); PG8_LDB(B1, 0, 1); PG8_SCHED; PG8_LDA(At, 0, 0); PG8_STAGE(PG8_SA(1, 1), a1 + hstep, voffA);
;             PG8_WAIT_V(8); PG8_WAIT_L(0); PG8_BAR; PG8_MMA(0, 0, At, B0); PG8_MMA(0, 1, At, B1); PG8_BAR; PG8_SCHED;
;             PG8_LDA(At, 0, 1); PG8_STAGE(PG8_SB(0, 0), b2, voffB); PG8_STAGE(PG8_SB(0, 1), b2 + hstep, voffB); PG8_STAGE(PG8_SA(0, 0), a2, voffA);
;             PG8_WAIT_V(8); PG8_WAIT_L(0); PG8_BAR; PG8_MMA(1, 0, At, B0); PG8_MMA(1, 1, At, B1); PG8_BAR; PG8_SCHED;
;             PG8_LDB(B0, 1, 0); PG8_LDB(B1, 1, 1); PG8_SCHED; PG8_LDA(At, 1, 0); PG8_STAGE(PG8_SA(0, 1), a2 + hstep, voffA);
;             PG8_WAIT_V(8); PG8_WAIT_L(0); PG8_BAR; PG8_MMA(0, 0, At, B0); PG8_MMA(0, 1, At, B1); PG8_BAR; PG8_SCHED;
;             PG8_LDA(At, 1, 1); PG8_STAGE(PG8_SB(1, 0), b3, voffB); PG8_STAGE(PG8_SB(1, 1), b3 + hstep, voffB); PG8_STAGE(PG8_SA(1, 0), a3, voffA);
;             PG8_WAIT_V(8); PG8_WAIT_L(0); PG8_BAR; PG8_MMA(1, 0, At, B0); PG8_MMA(1, 1, At, B1); PG8_BAR; PG8_SCHED;
	s_add_i32 s30, 0, 0x18000
	s_add_i32 s31, 0, 0x1c000
	ds_read_b128 v[130:133], v250 offset:32768
	ds_read_b128 v[134:137], v250 offset:33792
	ds_read_b128 v[138:141], v250 offset:34816
	ds_read_b128 v[142:145], v250 offset:35840
	ds_read_b128 v[146:149], v250 offset:49152
	ds_read_b128 v[150:153], v250 offset:50176
	ds_read_b128 v[154:157], v250 offset:51200
	ds_read_b128 v[158:161], v250 offset:52224
	s_add_u32 s4, s4, 0x80000
	s_addc_u32 s5, s5, 0
	s_mov_b32 m0, s69
	ds_read_b128 v[162:165], v209 offset:32768
	ds_read_b128 v[166:169], v209 offset:33792
	ds_read_b128 v[170:173], v209 offset:34816
	ds_read_b128 v[174:177], v209 offset:35840
	ds_read_b128 v[210:213], v209 offset:36864
	ds_read_b128 v[232:235], v209 offset:37888
	ds_read_b128 v[242:245], v209 offset:38912
	ds_read_b128 v[246:249], v209 offset:39936
	global_load_lds_dwordx4 v182, s[4:5]
	s_mov_b32 m0, s72
	s_nop 0
	global_load_lds_dwordx4 v180, s[4:5]
	s_waitcnt vmcnt(8)
	s_waitcnt lgkmcnt(0)
	s_barrier
	v_mfma_f32_16x16x32_bf16 v[126:129], v[130:133], v[162:165], v[126:129]
	v_mfma_f32_16x16x32_bf16 v[122:125], v[138:141], v[162:165], v[122:125]
	v_mfma_f32_16x16x32_bf16 v[110:113], v[130:133], v[170:173], v[110:113]
	v_mfma_f32_16x16x32_bf16 v[106:109], v[138:141], v[170:173], v[106:109]
	v_mfma_f32_16x16x32_bf16 v[92:95], v[130:133], v[210:213], v[92:95]
	v_mfma_f32_16x16x32_bf16 v[88:91], v[138:141], v[210:213], v[88:91]
	v_mfma_f32_16x16x32_bf16 v[76:79], v[130:133], v[242:245], v[76:79]
	v_mfma_f32_16x16x32_bf16 v[72:75], v[138:141], v[242:245], v[72:75]
	v_mfma_f32_16x16x32_bf16 v[126:129], v[134:137], v[166:169], v[126:129]
	v_mfma_f32_16x16x32_bf16 v[122:125], v[142:145], v[166:169], v[122:125]
	v_mfma_f32_16x16x32_bf16 v[110:113], v[134:137], v[174:177], v[110:113]
	v_mfma_f32_16x16x32_bf16 v[106:109], v[142:145], v[174:177], v[106:109]
	v_mfma_f32_16x16x32_bf16 v[92:95], v[134:137], v[232:235], v[92:95]
	v_mfma_f32_16x16x32_bf16 v[88:91], v[142:145], v[232:235], v[88:91]
	v_mfma_f32_16x16x32_bf16 v[76:79], v[134:137], v[246:249], v[76:79]
	v_mfma_f32_16x16x32_bf16 v[72:75], v[142:145], v[246:249], v[72:75]
	v_mfma_f32_16x16x32_bf16 v[118:121], v[146:149], v[162:165], v[118:121]
	v_mfma_f32_16x16x32_bf16 v[114:117], v[154:157], v[162:165], v[114:117]
	v_mfma_f32_16x16x32_bf16 v[102:105], v[146:149], v[170:173], v[102:105]
	v_mfma_f32_16x16x32_bf16 v[98:101], v[154:157], v[170:173], v[98:101]
	v_mfma_f32_16x16x32_bf16 v[84:87], v[146:149], v[210:213], v[84:87]
	v_mfma_f32_16x16x32_bf16 v[80:83], v[154:157], v[210:213], v[80:83]
	v_mfma_f32_16x16x32_bf16 v[68:71], v[146:149], v[242:245], v[68:71]
	v_mfma_f32_16x16x32_bf16 v[64:67], v[154:157], v[242:245], v[64:67]
	v_mfma_f32_16x16x32_bf16 v[118:121], v[150:153], v[166:169], v[118:121]
	v_mfma_f32_16x16x32_bf16 v[114:117], v[158:161], v[166:169], v[114:117]
	v_mfma_f32_16x16x32_bf16 v[102:105], v[150:153], v[174:177], v[102:105]
	v_mfma_f32_16x16x32_bf16 v[98:101], v[158:161], v[174:177], v[98:101]
	v_mfma_f32_16x16x32_bf16 v[84:87], v[150:153], v[232:235], v[84:87]
	v_mfma_f32_16x16x32_bf16 v[80:83], v[158:161], v[232:235], v[80:83]
	v_mfma_f32_16x16x32_bf16 v[68:71], v[150:153], v[246:249], v[68:71]
	v_mfma_f32_16x16x32_bf16 v[64:67], v[158:161], v[246:249], v[64:67]
	s_barrier
	s_add_i32 s4, s30, s28
	s_add_i32 m0, s4, 0xffffff80
	ds_read_b128 v[162:165], v209 offset:49152
	ds_read_b128 v[166:169], v209 offset:50176
	ds_read_b128 v[170:173], v209 offset:51200
	ds_read_b128 v[174:177], v209 offset:52224
	ds_read_b128 v[210:213], v209 offset:53248
	ds_read_b128 v[232:235], v209 offset:54272
	ds_read_b128 v[242:245], v209 offset:55296
	ds_read_b128 v[246:249], v209 offset:56320
	global_load_lds_dwordx4 v96, s[0:1] offset:128
	s_add_i32 m0, s4, 0x1f80
	s_add_i32 s4, s31, s28
	global_load_lds_dwordx4 v178, s[0:1] offset:128
	s_add_u32 s0, s0, 0x80080
	s_addc_u32 s1, s1, 0
	s_mov_b32 m0, s4
	s_nop 0
	global_load_lds_dwordx4 v96, s[0:1]
	s_add_i32 m0, s4, 0x2000
	s_nop 0
	global_load_lds_dwordx4 v178, s[0:1]
	v_lshl_add_u64 v[190:191], v[214:215], 0, s[20:21]
	s_mov_b32 m0, s74
	s_nop 0
	global_load_lds_dwordx4 v[190:191], off
	v_lshl_add_u64 v[190:191], v[228:229], 0, s[20:21]
	s_mov_b32 m0, s75
	s_nop 0
	global_load_lds_dwordx4 v[190:191], off
	s_waitcnt vmcnt(8)
	s_waitcnt lgkmcnt(0)
	s_barrier
	v_mfma_f32_16x16x32_bf16 v[60:63], v[130:133], v[162:165], v[60:63]
	v_mfma_f32_16x16x32_bf16 v[56:59], v[138:141], v[162:165], v[56:59]
	v_mfma_f32_16x16x32_bf16 v[44:47], v[130:133], v[170:173], v[44:47]
	v_mfma_f32_16x16x32_bf16 v[40:43], v[138:141], v[170:173], v[40:43]
	v_mfma_f32_16x16x32_bf16 v[28:31], v[130:133], v[210:213], v[28:31]
	v_mfma_f32_16x16x32_bf16 v[24:27], v[138:141], v[210:213], v[24:27]
	v_mfma_f32_16x16x32_bf16 v[12:15], v[130:133], v[242:245], v[12:15]
	v_mfma_f32_16x16x32_bf16 v[8:11], v[138:141], v[242:245], v[8:11]
	v_mfma_f32_16x16x32_bf16 v[60:63], v[134:137], v[166:169], v[60:63]
	v_mfma_f32_16x16x32_bf16 v[56:59], v[142:145], v[166:169], v[56:59]
	v_mfma_f32_16x16x32_bf16 v[44:47], v[134:137], v[174:177], v[44:47]
	v_mfma_f32_16x16x32_bf16 v[40:43], v[142:145], v[174:177], v[40:43]
	v_mfma_f32_16x16x32_bf16 v[28:31], v[134:137], v[232:235], v[28:31]
	v_mfma_f32_16x16x32_bf16 v[24:27], v[142:145], v[232:235], v[24:27]
	v_mfma_f32_16x16x32_bf16 v[12:15], v[134:137], v[246:249], v[12:15]
	v_mfma_f32_16x16x32_bf16 v[8:11], v[142:145], v[246:249], v[8:11]
	v_mfma_f32_16x16x32_bf16 v[52:55], v[146:149], v[162:165], v[52:55]
	v_mfma_f32_16x16x32_bf16 v[48:51], v[154:157], v[162:165], v[48:51]
	v_mfma_f32_16x16x32_bf16 v[36:39], v[146:149], v[170:173], v[36:39]
	v_mfma_f32_16x16x32_bf16 v[32:35], v[154:157], v[170:173], v[32:35]
	v_mfma_f32_16x16x32_bf16 v[20:23], v[146:149], v[210:213], v[20:23]
	v_mfma_f32_16x16x32_bf16 v[16:19], v[154:157], v[210:213], v[16:19]
	v_mfma_f32_16x16x32_bf16 v[4:7], v[146:149], v[242:245], v[4:7]
	v_mfma_f32_16x16x32_bf16 v[0:3], v[154:157], v[242:245], v[0:3]
	v_mfma_f32_16x16x32_bf16 v[52:55], v[150:153], v[166:169], v[52:55]
	v_mfma_f32_16x16x32_bf16 v[48:51], v[158:161], v[166:169], v[48:51]
	v_mfma_f32_16x16x32_bf16 v[36:39], v[150:153], v[174:177], v[36:39]
	v_mfma_f32_16x16x32_bf16 v[32:35], v[158:161], v[174:177], v[32:35]
	v_mfma_f32_16x16x32_bf16 v[20:23], v[150:153], v[232:235], v[20:23]
	v_mfma_f32_16x16x32_bf16 v[16:19], v[158:161], v[232:235], v[16:19]
	v_mfma_f32_16x16x32_bf16 v[4:7], v[150:153], v[246:249], v[4:7]
	v_mfma_f32_16x16x32_bf16 v[0:3], v[158:161], v[246:249], v[0:3]
	s_barrier
	s_add_i32 s19, s19, 2
	s_add_u32 s15, s15, 0x100
	s_addc_u32 s17, s17, 0
	s_add_u32 s40, s40, 0x100
	s_addc_u32 s41, s41, 0
	s_cmp_gt_u32 s19, 29
	s_cbranch_scc0 .LBB0_417
	s_and_b64 vcc, exec, s[34:35]
	s_cbranch_vccz .LBB0_420
	s_barrier
